# merge phase start delay grouped by XCD parity (bit0 of block id) instead of bit3
# baseline (speedup 1.0000x reference)
; __global__ void __launch_bounds__(NTHREADS, 2) fwd_kernel(Args A) {
;     ...
;         case 4: if (PMASK & 16) { pg8::Gemm g{(const bf16_t*)(ws + WS_Y), wl + WT_BR, Mx, DM, DM, 0, 0}; const bool coop = (ph_hi - ph_lo > 1);
;                   if (last) S.init(NLAT, DM, C.G, C.bid); else if (coop) S.init(NLAT, DM, C.G, C.bid, NCTX, 4); else S.init(MROWS, DM, C.G, C.bid);
;                   pg8::EpiMerge E{(const bf16_t*)(ws + WS_G), (bf16_t*)(ws + WS_MB), (float*)(ws + WS_PB)};
;                   pg8::gemm_phase<pg8::EpiMerge, true>(C.lds, C.tid, g, S, E);
.LBB0_242:
	v_readlane_b32 s100, v249, 56
	s_nop 3
	s_bitcmp1_b32 s100, 0
	s_cbranch_scc0 .Lmerge_nodelay
	s_sleep 127
	s_sleep 127
